# phase 0: S5 parameter items start first (on 3-item blocks) and their 16-step loop issues each iteration's loads together (1 drain instead of 7)
# speedup vs baseline: 1.0473x; 1.0115x over previous
; DEVINL int tidx() { int t = threadIdx.x; asm volatile("" : "+v"(t)); return t; }
; DEVINL int bidx() { int t = blockIdx.x; asm volatile("" : "+s"(t)); return t; }
; DEVINL void s5_param(const Params& p, int idx) {
;   const int g = idx >> 6, n = idx & 63;
;   float lre = fminf(p.a_re[idx], -1e-4f), lim = p.a_im[idx];
;   float dt = expf(p.log_dt[g]);
;   float mag = expf(lre * dt);
;   float ar = mag * cosf(lim * dt), ai = mag * sinf(lim * dt);
; DEVINL void phase0(const Params& p, char* smem) {
;   for (int it = bidx(); it < NTR_A + NXROW_ITEMS + 8; it += gridDim.x) {
;     if (it < NTR_A) {
;       tr_tile(p, smem, 0, it / 16, it % 16);
;     } else if (it < NTR_A + NXROW_ITEMS) {
;       xrow_prep<4>(p, (it - NTR_A) * 16 + (tidx() >> 6) * 4);
;     } else {
;       s5_param(p, (it - NTR_A - NXROW_ITEMS) * 256 + tidx());
.LBB0_1462:
	s_or_b64 exec, exec, s[36:37]
	s_waitcnt vmcnt(0)
	v_subrev_u32_e32 v196, 0x70, v1
	v_add_u32_e32 v197, 0x5f8, v1
	v_cmp_gt_u32_e32 vcc, 8, v196
	v_subrev_u32_e32 v196, 0x668, v1
	s_nop 0
	v_cndmask_b32_e32 v197, v1, v197, vcc
	v_cmp_gt_u32_e32 vcc, 8, v196
	v_subrev_u32_e32 v196, 0x5f8, v1
	s_nop 0
	v_cndmask_b32_e32 v1, v197, v196, vcc
	v_add_u32_e32 v1, v1, v104
	s_movk_i32 s0, 0x66f
	v_cmp_lt_i32_e32 vcc, s0, v1
	s_or_b64 s[40:41], vcc, s[40:41]
	s_andn2_b64 exec, exec, s[40:41]
	s_cbranch_execz .LBB0_1545
.LBB0_1463:
	v_subrev_u32_e32 v196, 0x70, v1
	v_add_u32_e32 v197, 0x5f8, v1
	v_cmp_gt_u32_e32 vcc, 8, v196
	v_subrev_u32_e32 v196, 0x668, v1
	s_nop 0
	v_cndmask_b32_e32 v197, v1, v197, vcc
	v_cmp_gt_u32_e32 vcc, 8, v196
	v_subrev_u32_e32 v196, 0x5f8, v1
	s_nop 0
	v_cndmask_b32_e32 v1, v197, v196, vcc
	s_movk_i32 s0, 0x21f
	v_cmp_lt_i32_e32 vcc, s0, v1
	s_and_saveexec_b64 s[0:1], vcc
	s_xor_b64 s[42:43], exec, s[0:1]
	s_cbranch_execz .LBB0_1517
	s_movk_i32 s0, 0x667
	v_cmp_lt_u32_e32 vcc, s0, v1
	s_and_saveexec_b64 s[0:1], vcc
	s_xor_b64 s[44:45], exec, s[0:1]
	s_cbranch_execz .LBB0_1475
	s_waitcnt vmcnt(0) lgkmcnt(0)
	v_lshlrev_b32_e32 v4, 8, v1
	v_mov_b32_e32 v3, v0
	s_mov_b32 s0, 0xfff99800
	s_nop 0
	v_add3_u32 v8, v4, v3, s0
	v_ashrrev_i32_e32 v14, 6, v8
	v_ashrrev_i32_e32 v9, 31, v8
	v_lshlrev_b64 v[6:7], 2, v[8:9]
	v_ashrrev_i32_e32 v15, 31, v14
	s_waitcnt lgkmcnt(0)
	v_lshl_add_u64 v[4:5], s[74:75], 0, v[6:7]
	v_lshl_add_u64 v[10:11], v[14:15], 2, s[8:9]
	global_load_dword v4, v[4:5], off
	v_lshl_add_u64 v[6:7], s[76:77], 0, v[6:7]
	global_load_dword v5, v[10:11], off
	s_mov_b32 s0, 0x3fb8aa3b
	global_load_dword v6, v[6:7], off
	s_waitcnt vmcnt(1)
	v_mul_f32_e32 v7, 0x3fb8aa3b, v5
	v_fma_f32 v10, v5, s0, -v7
	v_rndne_f32_e32 v11, v7
	v_fmac_f32_e32 v10, 0x32a5705f, v5
	v_sub_f32_e32 v7, v7, v11
	v_add_f32_e32 v7, v7, v10
	v_exp_f32_e32 v7, v7
	v_cvt_i32_f32_e32 v10, v11
	s_mov_b32 s0, 0xc2ce8ed0
	v_cmp_ngt_f32_e32 vcc, s0, v5
	s_mov_b32 s0, 0x42b17218
	v_ldexp_f32 v7, v7, v10
	v_cndmask_b32_e32 v7, 0, v7, vcc
	v_cmp_nlt_f32_e32 vcc, s0, v5
	s_brev_b32 s0, 18
	s_nop 0
	v_cndmask_b32_e32 v10, v127, v7, vcc
	s_waitcnt vmcnt(0)
	v_mul_f32_e32 v5, v6, v10
	v_and_b32_e32 v7, 0x7fffffff, v5
	v_cmp_nlt_f32_e64 s[46:47], |v5|, s0
	v_lshrrev_b32_e32 v16, 23, v7
	v_and_b32_e32 v13, 0x7fffff, v7
	s_and_saveexec_b64 s[0:1], s[46:47]
	s_xor_b64 s[66:67], exec, s[0:1]
	s_cbranch_execz .LBB0_1467
	v_add_u32_e32 v11, 0xffffff88, v16
	v_cmp_lt_u32_e32 vcc, 63, v11
	s_mov_b32 s0, 0xfe5163ab
	v_mov_b32_e32 v21, v2
	v_cndmask_b32_e32 v12, 0, v128, vcc
	v_add_u32_e32 v11, v12, v11
	v_cmp_lt_u32_e64 s[34:35], 31, v11
	v_mov_b32_e32 v23, v2
	v_mov_b32_e32 v25, v2
	v_cndmask_b32_e64 v12, 0, v129, s[34:35]
	v_add_u32_e32 v11, v12, v11
	v_cmp_lt_u32_e64 s[36:37], 31, v11
	v_mov_b32_e32 v27, v2
	v_mov_b32_e32 v29, v2
	v_cndmask_b32_e64 v12, 0, v129, s[36:37]
	v_add_u32_e32 v11, v12, v11
	v_or_b32_e32 v12, 0x800000, v13
	v_mad_u64_u32 v[18:19], s[0:1], v12, s0, 0
	v_mov_b32_e32 v20, v19
	s_mov_b32 s0, 0x3c439041
	v_mad_u64_u32 v[20:21], s[0:1], v12, s0, v[20:21]
	v_mov_b32_e32 v22, v21
	s_mov_b32 s0, 0xdb629599
	v_mad_u64_u32 v[22:23], s[0:1], v12, s0, v[22:23]
	v_mov_b32_e32 v24, v23
	s_mov_b32 s0, 0xf534ddc0
	v_mad_u64_u32 v[24:25], s[0:1], v12, s0, v[24:25]
	v_mov_b32_e32 v26, v25
	s_mov_b32 s0, 0xfc2757d1
	v_mad_u64_u32 v[26:27], s[0:1], v12, s0, v[26:27]
	v_mov_b32_e32 v28, v27
	s_mov_b32 s0, 0x4e441529
	v_mad_u64_u32 v[28:29], s[0:1], v12, s0, v[28:29]
	v_mov_b32_e32 v30, v29
	v_mov_b32_e32 v31, v2
	s_mov_b32 s0, 0xa2f9836e
	v_mad_u64_u32 v[30:31], s[0:1], v12, s0, v[30:31]
	v_cndmask_b32_e32 v17, v28, v24, vcc
	v_cndmask_b32_e32 v12, v30, v26, vcc
	v_cndmask_b32_e32 v21, v31, v28, vcc
	v_cndmask_b32_e64 v19, v12, v17, s[34:35]
	v_cndmask_b32_e64 v12, v21, v12, s[34:35]
	v_cndmask_b32_e32 v21, v26, v22, vcc
	v_cndmask_b32_e64 v17, v17, v21, s[34:35]
	v_cndmask_b32_e64 v12, v12, v19, s[36:37]
	v_cndmask_b32_e64 v19, v19, v17, s[36:37]
	v_sub_u32_e32 v23, 32, v11
	v_alignbit_b32 v25, v12, v19, v23
	v_cmp_eq_u32_e64 s[38:39], 0, v11
	v_cndmask_b32_e32 v18, v22, v18, vcc
	s_mov_b32 s0, 0x3fc90fda
	v_cndmask_b32_e64 v11, v25, v12, s[38:39]
	v_cndmask_b32_e32 v12, v24, v20, vcc
	v_cndmask_b32_e64 v20, v21, v12, s[34:35]
	v_cndmask_b32_e64 v17, v17, v20, s[36:37]
	v_alignbit_b32 v21, v19, v17, v23
	v_cndmask_b32_e64 v12, v12, v18, s[34:35]
	v_cndmask_b32_e64 v19, v21, v19, s[38:39]
	v_bfe_u32 v25, v11, 29, 1
	v_cndmask_b32_e64 v12, v20, v12, s[36:37]
	v_alignbit_b32 v21, v11, v19, 30
	v_sub_u32_e32 v26, 0, v25
	v_alignbit_b32 v18, v17, v12, v23
	v_xor_b32_e32 v21, v21, v26
	v_cndmask_b32_e64 v17, v18, v17, s[38:39]
	v_alignbit_b32 v18, v19, v17, 30
	v_ffbh_u32_e32 v19, v21
	v_min_u32_e32 v19, 32, v19
	v_alignbit_b32 v12, v17, v12, 30
	v_xor_b32_e32 v18, v18, v26
	v_sub_u32_e32 v20, 31, v19
	v_xor_b32_e32 v12, v12, v26
	v_alignbit_b32 v21, v21, v18, v20
	v_alignbit_b32 v12, v18, v12, v20
	v_alignbit_b32 v17, v21, v12, 9
	v_ffbh_u32_e32 v18, v17
	v_min_u32_e32 v18, 32, v18
	v_lshrrev_b32_e32 v24, 29, v11
	v_not_b32_e32 v20, v18
	v_alignbit_b32 v12, v17, v12, v20
	v_lshlrev_b32_e32 v17, 31, v24
	v_or_b32_e32 v20, 0x33000000, v17
	v_add_lshl_u32 v18, v18, v19, 23
	v_lshrrev_b32_e32 v12, 9, v12
	v_sub_u32_e32 v18, v20, v18
	v_or_b32_e32 v17, 0.5, v17
	v_lshlrev_b32_e32 v19, 23, v19
	v_or_b32_e32 v12, v18, v12
	v_lshrrev_b32_e32 v18, 9, v21
	v_sub_u32_e32 v17, v17, v19
	v_or_b32_e32 v17, v18, v17
	v_mul_f32_e32 v18, 0x3fc90fda, v17
	v_fma_f32 v19, v17, s0, -v18
	v_fmac_f32_e32 v19, 0x33a22168, v17
	v_fmac_f32_e32 v19, 0x3fc90fda, v12
	v_lshrrev_b32_e32 v11, 30, v11
	v_add_f32_e32 v12, v18, v19
	v_add_u32_e32 v11, v25, v11

; DEVINL void s5_param(const Params& p, int idx) {
;     ...
;   float lre = fminf(p.a_re[idx], -1e-4f), lim = p.a_im[idx];
;   float dt = expf(p.log_dt[g]);
;   float mag = expf(lre * dt);
;   float ar = mag * cosf(lim * dt), ai = mag * sinf(lim * dt);
;   float den = lre * lre + lim * lim;
;   float nr = ar - 1.f, ni = ai;
;   float fr = (nr * lre + ni * lim) / den, fi = (ni * lre - nr * lim) / den;
;   float* abar = (float*)(p.ws + OFF_ABAR);
;   abar[idx * 2] = ar; abar[idx * 2 + 1] = ai;
;   float p16r = ar, p16i = ai;
;   for (int e = 0; e < 4; ++e) csq(p16r, p16i);
;   float p256r = p16r, p256i = p16i;
;   for (int e = 0; e < 4; ++e) csq(p256r, p256i);
;   float* apw = (float*)(p.ws + OFF_APW);
;   apw[idx * 4 + 0] = p256r; apw[idx * 4 + 1] = p256i;
;   apw[idx * 4 + 2] = p256r * p16r - p256i * p16i; apw[idx * 4 + 3] = p256r * p16i + p256i * p16r;
.LBB0_1473:
	s_or_b64 exec, exec, s[0:1]
	v_max_f32_e32 v4, v4, v4
	v_min_f32_e32 v16, 0xb8d1b717, v4
	v_mul_f32_e32 v4, v16, v10
	v_mul_f32_e32 v10, 0x3fb8aa3b, v4
	s_mov_b32 s0, 0x3fb8aa3b
	v_fma_f32 v13, v4, s0, -v10
	v_rndne_f32_e32 v19, v10
	v_fmac_f32_e32 v13, 0x32a5705f, v4
	v_sub_f32_e32 v10, v10, v19
	v_add_f32_e32 v10, v10, v13
	v_cvt_i32_f32_e32 v13, v19
	v_exp_f32_e32 v10, v10
	s_mov_b32 s0, 0xc2ce8ed0
	v_cmp_ngt_f32_e32 vcc, s0, v4
	s_mov_b32 s0, 0x42b17218
	v_ldexp_f32 v10, v10, v13
	v_cndmask_b32_e32 v10, 0, v10, vcc
	v_cmp_nlt_f32_e32 vcc, s0, v4
	v_mul_f32_e32 v4, v12, v12
	s_brev_b32 s0, 1
	v_cndmask_b32_e32 v32, v127, v10, vcc
	v_fmamk_f32 v10, v4, 0xb94c1982, v97
	v_fmaak_f32 v10, v4, v10, 0xbe2aaa9d
	v_mul_f32_e32 v10, v4, v10
	v_fmac_f32_e32 v12, v12, v10
	v_fmamk_f32 v10, v4, 0x37d75334, v114
	v_fmaak_f32 v10, v4, v10, 0x3d2aabf7
	v_fmaak_f32 v10, v4, v10, 0xbf000004
	v_fma_f32 v4, v4, v10, 1.0
	v_and_b32_e32 v10, 1, v11
	v_cmp_eq_u32_e32 vcc, 0, v10
	v_lshlrev_b32_e32 v10, 30, v11
	s_mov_b32 s36, 1
	v_cndmask_b32_e64 v4, -v12, v4, vcc
	v_bitop3_b32 v4, v10, v4, s0 bitop3:0x6c
	s_movk_i32 s0, 0x1f8
	v_cmp_class_f32_e64 vcc, v5, s0
	v_xor_b32_e32 v5, v7, v5
	v_readlane_b32 s0, v194, 39
	v_cndmask_b32_e32 v33, v130, v4, vcc
	v_and_b32_e32 v4, 63, v3
	v_mul_f32_e32 v3, v18, v18
	v_fmamk_f32 v10, v3, 0xb94c1982, v97
	v_fmaak_f32 v10, v3, v10, 0xbe2aaa9d
	v_mul_f32_e32 v10, v3, v10
	v_fmac_f32_e32 v18, v18, v10
	v_fmamk_f32 v10, v3, 0x37d75334, v114
	v_fmaak_f32 v10, v3, v10, 0x3d2aabf7
	v_fmaak_f32 v10, v3, v10, 0xbf000004
	v_fma_f32 v3, v3, v10, 1.0
	v_and_b32_e32 v10, 1, v17
	v_cmp_eq_u32_e64 s[34:35], 0, v10
	v_lshlrev_b32_e32 v10, 30, v17
	v_and_b32_e32 v10, 0x80000000, v10
	v_cndmask_b32_e64 v3, v3, v18, s[34:35]
	v_xor_b32_e32 v5, v5, v10
	v_xor_b32_e32 v3, v5, v3
	v_lshlrev_b32_e32 v10, 1, v8
	v_cndmask_b32_e32 v3, v130, v3, vcc
	v_ashrrev_i32_e32 v11, 31, v10
	v_readlane_b32 s1, v194, 40
	v_mul_f32_e32 v20, v32, v33
	v_mul_f32_e32 v21, v32, v3
	v_lshl_add_u64 v[10:11], v[10:11], 2, s[0:1]
	global_store_dwordx2 v[10:11], v[20:21], off
	v_add_f32_e32 v11, v20, v20
	v_mul_f32_e32 v10, v21, v21
	v_pk_fma_f32 v[12:13], v[20:21], v[20:21], v[10:11] op_sel_hi:[1,1,0] neg_lo:[0,0,1] neg_hi:[0,0,1]
	v_readlane_b32 s0, v194, 51
	v_mov_b32_e32 v10, v12
	v_mov_b32_e32 v20, v12
	v_pk_mul_f32 v[10:11], v[10:11], v[20:21]
	v_readlane_b32 s1, v194, 52
	v_pk_mov_b32 v[12:13], v[10:11], v[12:13] op_sel:[1,0]
	v_mov_b32_e32 v102, v11
	v_pk_mul_f32 v[18:19], v[12:13], v[102:103]
	v_pk_fma_f32 v[12:13], v[12:13], v[102:103], v[10:11] neg_lo:[1,0,0] neg_hi:[1,0,0]
	v_pk_mul_f32 v[22:23], v[10:11], v[18:19]
	v_pk_mov_b32 v[10:11], v[10:11], v[12:13] op_sel:[1,0]
	v_mov_b32_e32 v102, v19
	v_pk_mul_f32 v[10:11], v[10:11], v[102:103]
	v_mov_b32_e32 v24, v12
	v_mov_b32_e32 v25, v23
	v_mov_b32_e32 v13, v11
	v_pk_mul_f32 v[12:13], v[24:25], v[12:13]
	v_pk_mul_f32 v[18:19], v[22:23], v[10:11] op_sel:[1,0]
	v_pk_fma_f32 v[10:11], v[22:23], v[10:11], v[12:13] op_sel:[1,0,0] neg_lo:[1,0,0] neg_hi:[1,0,0]
	v_pk_mul_f32 v[18:19], v[12:13], v[18:19]
	v_add_f32_e32 v12, v10, v10
	v_mov_b32_e32 v11, v19
	v_pk_fma_f32 v[18:19], v[10:11], v[10:11], v[18:19] op_sel:[0,0,1] op_sel_hi:[1,1,0] neg_lo:[0,0,1] neg_hi:[0,0,1]
	v_mov_b32_e32 v102, v13
	v_mov_b32_e32 v13, v18
	v_pk_mul_f32 v[24:25], v[102:103], v[12:13]
	v_mov_b32_e32 v10, v18
	v_mov_b32_e32 v11, v24
	v_pk_mul_f32 v[10:11], v[10:11], v[10:11]
	v_mov_b32_e32 v13, v24
	v_mov_b32_e32 v12, v10
	v_mov_b32_e32 v10, v11
	v_mov_b32_e32 v11, v25
	v_pk_add_f32 v[26:27], v[12:13], v[10:11] neg_lo:[0,1] neg_hi:[0,1]
	v_pk_mul_f32 v[10:11], v[12:13], v[10:11]
	v_mul_f32_e32 v12, v26, v26
	v_mov_b32_e32 v27, v11
	v_pk_fma_f32 v[12:13], v[26:27], v[26:27], v[12:13] op_sel_hi:[1,1,0] neg_lo:[1,0,0] neg_hi:[1,0,0]
	v_add_f32_e32 v10, v26, v26
	v_mov_b32_e32 v26, v11
	v_mov_b32_e32 v27, v13
	v_mov_b32_e32 v11, v13
	v_pk_mul_f32 v[10:11], v[26:27], v[10:11]
	v_mov_b32_e32 v26, v103
	v_pk_mov_b32 v[12:13], v[12:13], v[10:11] op_sel:[1,0]
	v_mov_b32_e32 v27, v10
	v_pk_mul_f32 v[28:29], v[12:13], v[26:27]
	v_pk_fma_f32 v[12:13], v[12:13], v[26:27], v[10:11] neg_lo:[1,0,0] neg_hi:[1,0,0]
	v_pk_mul_f32 v[28:29], v[10:11], v[28:29]
	v_add_f32_e32 v3, v13, v13
	v_mov_b32_e32 v29, v13
	v_mul_f32_e32 v10, v13, v13
	v_mul_f32_e32 v25, v28, v3
	v_pk_fma_f32 v[10:11], v[28:29], v[28:29], v[10:11] op_sel_hi:[1,1,0] neg_lo:[1,0,0] neg_hi:[1,0,0]
	v_mov_b32_e32 v30, v25
	v_mov_b32_e32 v31, v18
	v_lshlrev_b32_e32 v22, 2, v8
	v_mov_b32_e32 v12, v18
	v_mov_b32_e32 v13, v10
	v_mov_b32_e32 v26, v10
	v_mov_b32_e32 v27, v24
	v_pk_mul_f32 v[28:29], v[18:19], v[10:11]
	v_pk_mul_f32 v[18:19], v[24:25], v[30:31]
	v_ashrrev_i32_e32 v23, 31, v22
	v_pk_fma_f32 v[12:13], v[12:13], v[26:27], v[18:19]
	v_lshl_add_u64 v[22:23], v[22:23], 2, s[0:1]
	v_sub_f32_e32 v12, v28, v18
	v_mov_b32_e32 v11, v25
	global_store_dwordx4 v[22:23], v[10:13], off
	v_fma_f32 v18, v32, v33, -1.0
	v_mov_b32_e32 v22, v21
	v_mov_b32_e32 v23, v16
	v_mov_b32_e32 v19, v6
	v_readlane_b32 s0, v194, 41
	v_pk_mul_f32 v[22:23], v[16:17], v[22:23] op_sel_hi:[0,1]
	v_pk_mul_f32 v[24:25], v[6:7], v[18:19] op_sel_hi:[0,1]
	v_lshlrev_b64 v[10:11], 12, v[14:15]
	v_readlane_b32 s1, v194, 42
	v_sub_f32_e32 v3, v22, v24
	v_add_f32_e32 v5, v23, v25
	v_lshl_add_u64 v[10:11], s[0:1], 0, v[10:11]
	v_div_scale_f32 v7, s[0:1], v5, v5, v3
	v_rcp_f32_e32 v20, v7
	v_lshlrev_b32_e32 v12, 6, v4
	v_mov_b32_e32 v13, v2
	v_readlane_b32 s0, v194, 43
	v_fma_f32 v17, -v7, v20, 1.0
	v_fmac_f32_e32 v20, v17, v20
	v_div_scale_f32 v17, vcc, v3, v5, v3
	v_mul_f32_e32 v22, v17, v20
	v_fma_f32 v19, -v7, v22, v17
; DEVINL u16 f2bf(float f) { return (u16)((__float_as_uint(f) + 0x8000u) >> 16); }
; DEVINL void s5_param(const Params& p, int idx) {
;     ...
;   float den = lre * lre + lim * lim;
;   float nr = ar - 1.f, ni = ai;
;   float fr = (nr * lre + ni * lim) / den, fi = (ni * lre - nr * lim) / den;
;   float* abar = (float*)(p.ws + OFF_ABAR);
;   abar[idx * 2] = ar; abar[idx * 2 + 1] = ai;
;   float p16r = ar, p16i = ai;
;   for (int e = 0; e < 4; ++e) csq(p16r, p16i);
;   float p256r = p16r, p256i = p16i;
;   for (int e = 0; e < 4; ++e) csq(p256r, p256i);
;   float* apw = (float*)(p.ws + OFF_APW);
;   apw[idx * 4 + 0] = p256r; apw[idx * 4 + 1] = p256i;
;   apw[idx * 4 + 2] = p256r * p16r - p256i * p16i; apw[idx * 4 + 3] = p256r * p16i + p256i * p16r;
;   u16* bbt = (u16*)(p.ws + OFF_BBT);
;   u16* ct = (u16*)(p.ws + OFF_CT);
;   for (int j = 0; j < 16; ++j) {
;     float br = p.b_re[(size_t)idx * 16 + j], bi = p.b_im[(size_t)idx * 16 + j];
;     bbt[((size_t)g * 128 + 2 * n) * 16 + j] = f2bf(fr * br - fi * bi);
;     bbt[((size_t)g * 128 + 2 * n + 1) * 16 + j] = f2bf(fr * bi + fi * br);
;     ct[((size_t)g * 16 + j) * 128 + 2 * n] = f2bf(p.c_re[((size_t)g * 16 + j) * 64 + n]);
;     ct[((size_t)g * 16 + j) * 128 + 2 * n + 1] = f2bf(-p.c_im[((size_t)g * 16 + j) * 64 + n]);
;   }
	v_fmac_f32_e32 v22, v19, v20
	v_fma_f32 v23, -v7, v22, v17
	v_mov_b32_e32 v17, v6
	v_mov_b32_e32 v19, v21
	v_pk_mul_f32 v[6:7], v[16:17], v[18:19]
	v_lshl_add_u64 v[10:11], v[10:11], 0, v[12:13]
	v_lshlrev_b32_e32 v12, 2, v4
	v_readlane_b32 s1, v194, 44
	v_add_f32_e32 v6, v6, v7
	v_div_fmas_f32 v16, v23, v20, v22
	v_lshl_add_u64 v[12:13], s[0:1], 0, v[12:13]
	v_div_scale_f32 v7, s[0:1], v5, v5, v6
	v_rcp_f32_e32 v17, v7
	v_div_fixup_f32 v16, v16, v5, v3
	v_lshlrev_b64 v[14:15], 4, v[14:15]
	s_mov_b32 s14, 0
	v_fma_f32 v3, -v7, v17, 1.0
	v_fmac_f32_e32 v17, v3, v17
	v_div_scale_f32 v3, vcc, v6, v5, v6
	v_mul_f32_e32 v18, v3, v17
	v_fma_f32 v19, -v7, v18, v3
	v_fmac_f32_e32 v18, v19, v17
	v_fma_f32 v3, -v7, v18, v3
	v_div_fmas_f32 v3, v3, v17, v18
	v_div_fixup_f32 v18, v3, v5, v6
	v_lshlrev_b64 v[8:9], 4, v[8:9]
	v_mov_b32_e32 v19, v18
	v_mov_b32_e32 v17, v16
	v_mov_b32_e32 v20, v14
	v_mov_b32_e32 v21, v15
	v_mov_b32_e32 v6, v4
	s_mov_b32 s0, 16
	v_lshlrev_b64 v[206:207], 8, v[14:15]
	v_lshlrev_b32_e32 v205, 2, v4
	v_or_b32_e32 v206, v206, v205
	v_lshl_add_u64 v[208:209], s[82:83], 0, v[206:207]
	v_lshl_add_u64 v[206:207], s[4:5], 0, v[206:207]
	global_load_dword v204, v[208:209], off
	global_load_dword v204, v[208:209], off offset:256
	global_load_dword v204, v[208:209], off offset:512
	global_load_dword v204, v[208:209], off offset:768
	global_load_dword v204, v[208:209], off offset:1024
	global_load_dword v204, v[208:209], off offset:1280
	global_load_dword v204, v[208:209], off offset:1536
	global_load_dword v204, v[208:209], off offset:1792
	global_load_dword v204, v[208:209], off offset:2048
	global_load_dword v204, v[208:209], off offset:2304
	global_load_dword v204, v[208:209], off offset:2560
	global_load_dword v204, v[208:209], off offset:2816
	global_load_dword v204, v[208:209], off offset:3072
	global_load_dword v204, v[208:209], off offset:3328
	global_load_dword v204, v[208:209], off offset:3584
	global_load_dword v204, v[208:209], off offset:3840
	global_load_dword v204, v[206:207], off
	global_load_dword v204, v[206:207], off offset:256
	global_load_dword v204, v[206:207], off offset:512
	global_load_dword v204, v[206:207], off offset:768
	global_load_dword v204, v[206:207], off offset:1024
	global_load_dword v204, v[206:207], off offset:1280
	global_load_dword v204, v[206:207], off offset:1536
	global_load_dword v204, v[206:207], off offset:1792
	global_load_dword v204, v[206:207], off offset:2048
	global_load_dword v204, v[206:207], off offset:2304
	global_load_dword v204, v[206:207], off offset:2560
	global_load_dword v204, v[206:207], off offset:2816
	global_load_dword v204, v[206:207], off offset:3072
	global_load_dword v204, v[206:207], off offset:3328
	global_load_dword v204, v[206:207], off offset:3584
	global_load_dword v204, v[206:207], off offset:3840
	v_lshlrev_b64 v[206:207], 2, v[8:9]
	v_lshl_add_u64 v[208:209], s[80:81], 0, v[206:207]
	global_load_dword v204, v[208:209], off
	global_load_dword v204, v[208:209], off offset:32
	v_lshl_add_u64 v[208:209], s[78:79], 0, v[206:207]
	global_load_dword v204, v[208:209], off
	global_load_dword v204, v[208:209], off offset:32
; DEVINL u16 f2bf(float f) { return (u16)((__float_as_uint(f) + 0x8000u) >> 16); }
; DEVINL void s5_param(const Params& p, int idx) {
;     ...
;   for (int j = 0; j < 16; ++j) {
;     float br = p.b_re[(size_t)idx * 16 + j], bi = p.b_im[(size_t)idx * 16 + j];
;     bbt[((size_t)g * 128 + 2 * n) * 16 + j] = f2bf(fr * br - fi * bi);
;     bbt[((size_t)g * 128 + 2 * n + 1) * 16 + j] = f2bf(fr * bi + fi * br);
;     ct[((size_t)g * 16 + j) * 128 + 2 * n] = f2bf(p.c_re[((size_t)g * 16 + j) * 64 + n]);
;     ct[((size_t)g * 16 + j) * 128 + 2 * n + 1] = f2bf(-p.c_im[((size_t)g * 16 + j) * 64 + n]);
;   }
.LBB0_1474:
	v_lshl_add_u64 v[206:207], v[8:9], 0, s[14:15]
	v_lshlrev_b64 v[206:207], 2, v[206:207]
	v_lshl_add_u64 v[208:209], s[80:81], 0, v[206:207]
	global_load_dwordx4 v[210:213], v[208:209], off
	v_lshl_add_u64 v[208:209], s[78:79], 0, v[206:207]
	global_load_dwordx4 v[214:217], v[208:209], off
	v_lshl_add_u64 v[206:207], v[14:15], 0, s[14:15]
	v_lshlrev_b64 v[206:207], 8, v[206:207]
	v_lshlrev_b32_e32 v205, 2, v4
	v_or_b32_e32 v206, v206, v205
	v_lshl_add_u64 v[208:209], s[82:83], 0, v[206:207]
	global_load_dword v218, v[208:209], off
	global_load_dword v219, v[208:209], off offset:256
	global_load_dword v220, v[208:209], off offset:512
	global_load_dword v221, v[208:209], off offset:768
	v_lshl_add_u64 v[208:209], s[4:5], 0, v[206:207]
	global_load_dword v222, v[208:209], off
	global_load_dword v223, v[208:209], off offset:256
	global_load_dword v224, v[208:209], off offset:512
	global_load_dword v225, v[208:209], off offset:768
	s_waitcnt vmcnt(0)
	v_lshl_add_u64 v[22:23], v[8:9], 0, s[14:15]
	v_lshlrev_b64 v[22:23], 2, v[22:23]
	v_lshl_add_u64 v[24:25], s[78:79], 0, v[22:23]
	v_lshl_add_u64 v[22:23], s[80:81], 0, v[22:23]
	v_mov_b32_e32 v22, v210
	v_mov_b32_e32 v23, v211
	s_mov_b32 s37, s15
	v_mov_b32_e32 v24, v214
	v_mov_b32_e32 v25, v215
	s_add_i32 s38, s14, 2
	s_mov_b32 s39, s15
	s_add_i32 s34, s36, 2
	s_mov_b32 s35, s15
	s_add_i32 s0, s0, -4
	v_pk_mul_f32 v[26:27], v[16:17], v[22:23]
	v_pk_mul_f32 v[22:23], v[18:19], v[22:23]
	v_pk_fma_f32 v[26:27], v[18:19], v[24:25], v[26:27] neg_lo:[0,0,1] neg_hi:[0,0,1]
	v_pk_fma_f32 v[22:23], v[16:17], v[24:25], v[22:23]
	v_add_u32_e32 v3, 0x8000, v26
	v_add_u32_e32 v5, 0x8000, v27
	v_perm_b32 v3, v5, v3, s25
	v_lshl_add_u64 v[26:27], s[14:15], 1, v[10:11]
	global_store_dword v[26:27], v3, off
	v_add_u32_e32 v3, 0x8000, v22
	v_add_u32_e32 v5, 0x8000, v23
	v_perm_b32 v3, v5, v3, s25
	v_lshl_add_u64 v[24:25], v[14:15], 0, s[14:15]
	global_store_dword v[26:27], v3, off offset:32
	v_lshl_add_u64 v[22:23], v[20:21], 0, s[36:37]
	v_lshlrev_b64 v[24:25], 8, v[24:25]
	v_lshlrev_b32_e32 v3, 2, v4
	v_or_b32_e32 v26, v24, v3
	v_mov_b32_e32 v27, v25
	v_lshlrev_b64 v[22:23], 8, v[22:23]
	v_lshlrev_b32_e32 v5, 2, v6
	v_lshl_add_u64 v[28:29], s[82:83], 0, v[26:27]
	v_or_b32_e32 v30, v22, v5
	v_mov_b32_e32 v31, v23
	v_lshl_add_u64 v[32:33], s[82:83], 0, v[30:31]
	v_mov_b32_e32 v7, v218
	s_nop 0
	v_mov_b32_e32 v28, v219
	v_lshl_add_u64 v[24:25], v[12:13], 0, v[24:25]
	v_lshl_add_u64 v[22:23], v[12:13], 0, v[22:23]
	v_lshl_add_u64 v[26:27], s[4:5], 0, v[26:27]
	s_add_i32 s14, s14, 4
	s_add_i32 s36, s36, 4
	s_cmp_lg_u32 s0, 0
	v_add_u32_e32 v7, 0x8000, v7
	v_add_u32_e32 v28, 0x8000, v28
	global_store_short_d16_hi v[24:25], v7, off
	global_store_short_d16_hi v[22:23], v28, off
	v_lshl_add_u64 v[28:29], s[4:5], 0, v[30:31]
	v_mov_b32_e32 v26, v222
	s_nop 0
	v_mov_b32_e32 v27, v223
	v_pk_add_f32 v[26:27], v[26:27], 0 neg_lo:[1,1] neg_hi:[1,1]
	s_nop 0
	v_add_u32_e32 v26, 0x8000, v26
	v_add_u32_e32 v7, 0x8000, v27
	global_store_short_d16_hi v[24:25], v26, off offset:2
	global_store_short_d16_hi v[22:23], v7, off offset:2
	v_lshl_add_u64 v[22:23], v[8:9], 0, s[38:39]
	v_lshlrev_b64 v[22:23], 2, v[22:23]
	v_lshl_add_u64 v[24:25], s[78:79], 0, v[22:23]
	v_lshl_add_u64 v[22:23], s[80:81], 0, v[22:23]
	v_mov_b32_e32 v22, v212
	v_mov_b32_e32 v23, v213
	v_pk_mul_f32 v[26:27], v[16:17], v[22:23]
	v_mov_b32_e32 v24, v216
	v_mov_b32_e32 v25, v217
	v_pk_mul_f32 v[22:23], v[18:19], v[22:23]
	v_pk_fma_f32 v[26:27], v[18:19], v[24:25], v[26:27] neg_lo:[0,0,1] neg_hi:[0,0,1]
	s_nop 0
	v_add_u32_e32 v7, 0x8000, v26
	v_add_u32_e32 v26, 0x8000, v27
	v_perm_b32 v7, v26, v7, s25
	v_lshl_add_u64 v[26:27], s[38:39], 1, v[10:11]
	v_pk_fma_f32 v[22:23], v[16:17], v[24:25], v[22:23]
	global_store_dword v[26:27], v7, off
	v_add_u32_e32 v7, 0x8000, v22
	v_add_u32_e32 v22, 0x8000, v23
	v_lshl_add_u64 v[24:25], v[14:15], 0, s[38:39]
	v_perm_b32 v7, v22, v7, s25
	v_lshl_add_u64 v[22:23], v[20:21], 0, s[34:35]
	v_lshlrev_b64 v[24:25], 8, v[24:25]
	global_store_dword v[26:27], v7, off offset:32
	v_or_b32_e32 v26, v24, v3
	v_mov_b32_e32 v27, v25
	v_lshlrev_b64 v[22:23], 8, v[22:23]
	v_lshl_add_u64 v[28:29], s[82:83], 0, v[26:27]
	v_or_b32_e32 v30, v22, v5
	v_mov_b32_e32 v31, v23
	v_lshl_add_u64 v[32:33], s[82:83], 0, v[30:31]
	v_mov_b32_e32 v3, v220
	v_mov_b32_e32 v5, v221
	v_lshl_add_u64 v[24:25], v[12:13], 0, v[24:25]
	v_lshl_add_u64 v[22:23], v[12:13], 0, v[22:23]
	v_lshl_add_u64 v[26:27], s[4:5], 0, v[26:27]
	v_lshl_add_u64 v[28:29], s[4:5], 0, v[30:31]
	v_add_u32_e32 v3, 0x8000, v3
	v_add_u32_e32 v5, 0x8000, v5
	global_store_short_d16_hi v[24:25], v3, off
	global_store_short_d16_hi v[22:23], v5, off
	v_mov_b32_e32 v26, v224
	s_nop 0
	v_mov_b32_e32 v27, v225
	v_pk_add_f32 v[26:27], v[26:27], 0 neg_lo:[1,1] neg_hi:[1,1]
	s_nop 0
	v_add_u32_e32 v5, 0x8000, v26
	v_add_u32_e32 v3, 0x8000, v27
	global_store_short_d16_hi v[24:25], v5, off offset:2
	global_store_short_d16_hi v[22:23], v3, off offset:2
	s_cbranch_scc1 .LBB0_1474
